# code placement: GEMM K-loop heads and diff loop bodies aligned to 64-byte instruction-cache lines (measurement 1)
# speedup vs baseline: 1.0061x; 1.0050x over previous
.LBB0_293:
	s_ashr_i32 s17, s16, 31
	s_lshl_b64 s[18:19], s[16:17], 19
	s_add_u32 s18, s3, s18
	s_addc_u32 s19, s30, s19
	s_and_b64 s[20:21], s[4:5], exec
	s_cselect_b32 s17, s19, s25
	s_cselect_b32 s47, s18, s24
	s_ashr_i32 s15, s14, 31
	s_lshl_b64 s[20:21], s[14:15], 19
	s_add_u32 s20, s31, s20
	s_addc_u32 s21, s33, s21
	s_and_b64 s[28:29], s[4:5], exec
	s_cselect_b32 s15, s21, s27
	s_cselect_b32 s48, s20, s26
	s_add_u32 s24, s24, 0x40080
	s_addc_u32 s25, s25, 0
	s_add_u32 s49, s26, 0x100
	v_mov_b32_e32 v2, 0
	s_addc_u32 s50, s27, 0
	s_mov_b32 s51, -2
	v_mov_b32_e32 v3, v2
	v_mov_b32_e32 v4, v2
	v_mov_b32_e32 v5, v2
	v_mov_b32_e32 v6, v2
	v_mov_b32_e32 v7, v2
	v_mov_b32_e32 v8, v2
	v_mov_b32_e32 v9, v2
	v_mov_b32_e32 v18, v2
	v_mov_b32_e32 v19, v2
	v_mov_b32_e32 v20, v2
	v_mov_b32_e32 v21, v2
	v_mov_b32_e32 v22, v2
	v_mov_b32_e32 v23, v2
	v_mov_b32_e32 v24, v2
	v_mov_b32_e32 v25, v2
	v_mov_b32_e32 v34, v2
	v_mov_b32_e32 v35, v2
	v_mov_b32_e32 v36, v2
	v_mov_b32_e32 v37, v2
	v_mov_b32_e32 v38, v2
	v_mov_b32_e32 v39, v2
	v_mov_b32_e32 v40, v2
	v_mov_b32_e32 v41, v2
	v_mov_b32_e32 v50, v2
	v_mov_b32_e32 v51, v2
	v_mov_b32_e32 v52, v2
	v_mov_b32_e32 v53, v2
	v_mov_b32_e32 v54, v2
	v_mov_b32_e32 v55, v2
	v_mov_b32_e32 v56, v2
	v_mov_b32_e32 v57, v2
	v_mov_b32_e32 v10, v2
	v_mov_b32_e32 v11, v2
	v_mov_b32_e32 v12, v2
	v_mov_b32_e32 v13, v2
	v_mov_b32_e32 v14, v2
	v_mov_b32_e32 v15, v2
	v_mov_b32_e32 v16, v2
	v_mov_b32_e32 v17, v2
	v_mov_b32_e32 v26, v2
	v_mov_b32_e32 v27, v2
	v_mov_b32_e32 v28, v2
	v_mov_b32_e32 v29, v2
	v_mov_b32_e32 v30, v2
	v_mov_b32_e32 v31, v2
	v_mov_b32_e32 v32, v2
	v_mov_b32_e32 v33, v2
	v_mov_b32_e32 v42, v2
	v_mov_b32_e32 v43, v2
	v_mov_b32_e32 v44, v2
	v_mov_b32_e32 v45, v2
	v_mov_b32_e32 v46, v2
	v_mov_b32_e32 v47, v2
	v_mov_b32_e32 v48, v2
	v_mov_b32_e32 v49, v2
	v_mov_b32_e32 v58, v2
	v_mov_b32_e32 v59, v2
	v_mov_b32_e32 v60, v2
	v_mov_b32_e32 v61, v2
	v_mov_b32_e32 v62, v2
	v_mov_b32_e32 v63, v2
	v_mov_b32_e32 v64, v2
	v_mov_b32_e32 v65, v2
	v_mov_b32_e32 v66, v2
	v_mov_b32_e32 v67, v2
	v_mov_b32_e32 v68, v2
	v_mov_b32_e32 v69, v2
	v_mov_b32_e32 v70, v2
	v_mov_b32_e32 v71, v2
	v_mov_b32_e32 v72, v2
	v_mov_b32_e32 v73, v2
	v_mov_b32_e32 v82, v2
	v_mov_b32_e32 v83, v2
	v_mov_b32_e32 v84, v2
	v_mov_b32_e32 v85, v2
	v_mov_b32_e32 v86, v2
	v_mov_b32_e32 v87, v2
	v_mov_b32_e32 v88, v2
	v_mov_b32_e32 v89, v2
	v_mov_b32_e32 v98, v2
	v_mov_b32_e32 v99, v2
	v_mov_b32_e32 v100, v2
	v_mov_b32_e32 v101, v2
	v_mov_b32_e32 v102, v2
	v_mov_b32_e32 v103, v2
	v_mov_b32_e32 v104, v2
	v_mov_b32_e32 v105, v2
	v_mov_b32_e32 v114, v2
	v_mov_b32_e32 v115, v2
	v_mov_b32_e32 v116, v2
	v_mov_b32_e32 v117, v2
	v_mov_b32_e32 v118, v2
	v_mov_b32_e32 v119, v2
	v_mov_b32_e32 v120, v2
	v_mov_b32_e32 v121, v2
	v_mov_b32_e32 v74, v2
	v_mov_b32_e32 v75, v2
	v_mov_b32_e32 v76, v2
	v_mov_b32_e32 v77, v2
	v_mov_b32_e32 v78, v2
	v_mov_b32_e32 v79, v2
	v_mov_b32_e32 v80, v2
	v_mov_b32_e32 v81, v2
	v_mov_b32_e32 v90, v2
	v_mov_b32_e32 v91, v2
	v_mov_b32_e32 v92, v2
	v_mov_b32_e32 v93, v2
	v_mov_b32_e32 v94, v2
	v_mov_b32_e32 v95, v2
	v_mov_b32_e32 v96, v2
	v_mov_b32_e32 v97, v2
	v_mov_b32_e32 v106, v2
	v_mov_b32_e32 v107, v2
	v_mov_b32_e32 v108, v2
	v_mov_b32_e32 v109, v2
	v_mov_b32_e32 v110, v2
	v_mov_b32_e32 v111, v2
	v_mov_b32_e32 v112, v2
	v_mov_b32_e32 v113, v2
	v_mov_b32_e32 v122, v2
	v_mov_b32_e32 v123, v2
	v_mov_b32_e32 v124, v2
	v_mov_b32_e32 v125, v2
	v_mov_b32_e32 v126, v2
	v_mov_b32_e32 v127, v2
	v_mov_b32_e32 v128, v2
	v_mov_b32_e32 v129, v2
	.p2align	6

.LBB0_390:
	s_add_u32 s2, s22, 0x100
	v_mov_b32_e32 v2, 0
	s_addc_u32 s49, s23, 0
	s_mov_b32 s50, -2
	v_mov_b32_e32 v3, v2
	v_mov_b32_e32 v4, v2
	v_mov_b32_e32 v5, v2
	v_mov_b32_e32 v6, v2
	v_mov_b32_e32 v7, v2
	v_mov_b32_e32 v8, v2
	v_mov_b32_e32 v9, v2
	v_mov_b32_e32 v10, v2
	v_mov_b32_e32 v11, v2
	v_mov_b32_e32 v12, v2
	v_mov_b32_e32 v13, v2
	v_mov_b32_e32 v22, v2
	v_mov_b32_e32 v23, v2
	v_mov_b32_e32 v24, v2
	v_mov_b32_e32 v25, v2
	v_mov_b32_e32 v26, v2
	v_mov_b32_e32 v27, v2
	v_mov_b32_e32 v28, v2
	v_mov_b32_e32 v29, v2
	v_mov_b32_e32 v38, v2
	v_mov_b32_e32 v39, v2
	v_mov_b32_e32 v40, v2
	v_mov_b32_e32 v41, v2
	v_mov_b32_e32 v42, v2
	v_mov_b32_e32 v43, v2
	v_mov_b32_e32 v44, v2
	v_mov_b32_e32 v45, v2
	v_mov_b32_e32 v54, v2
	v_mov_b32_e32 v55, v2
	v_mov_b32_e32 v56, v2
	v_mov_b32_e32 v57, v2
	v_mov_b32_e32 v14, v2
	v_mov_b32_e32 v15, v2
	v_mov_b32_e32 v16, v2
	v_mov_b32_e32 v17, v2
	v_mov_b32_e32 v18, v2
	v_mov_b32_e32 v19, v2
	v_mov_b32_e32 v20, v2
	v_mov_b32_e32 v21, v2
	v_mov_b32_e32 v30, v2
	v_mov_b32_e32 v31, v2
	v_mov_b32_e32 v32, v2
	v_mov_b32_e32 v33, v2
	v_mov_b32_e32 v34, v2
	v_mov_b32_e32 v35, v2
	v_mov_b32_e32 v36, v2
	v_mov_b32_e32 v37, v2
	v_mov_b32_e32 v46, v2
	v_mov_b32_e32 v47, v2
	v_mov_b32_e32 v48, v2
	v_mov_b32_e32 v49, v2
	v_mov_b32_e32 v50, v2
	v_mov_b32_e32 v51, v2
	v_mov_b32_e32 v52, v2
	v_mov_b32_e32 v53, v2
	v_mov_b32_e32 v58, v2
	v_mov_b32_e32 v59, v2
	v_mov_b32_e32 v60, v2
	v_mov_b32_e32 v61, v2
	v_mov_b32_e32 v62, v2
	v_mov_b32_e32 v63, v2
	v_mov_b32_e32 v64, v2
	v_mov_b32_e32 v65, v2
	v_mov_b32_e32 v66, v2
	v_mov_b32_e32 v67, v2
	v_mov_b32_e32 v68, v2
	v_mov_b32_e32 v69, v2
	v_mov_b32_e32 v70, v2
	v_mov_b32_e32 v71, v2
	v_mov_b32_e32 v72, v2
	v_mov_b32_e32 v73, v2
	v_mov_b32_e32 v74, v2
	v_mov_b32_e32 v75, v2
	v_mov_b32_e32 v76, v2
	v_mov_b32_e32 v77, v2
	v_mov_b32_e32 v86, v2
	v_mov_b32_e32 v87, v2
	v_mov_b32_e32 v88, v2
	v_mov_b32_e32 v89, v2
	v_mov_b32_e32 v90, v2
	v_mov_b32_e32 v91, v2
	v_mov_b32_e32 v92, v2
	v_mov_b32_e32 v93, v2
	v_mov_b32_e32 v102, v2
	v_mov_b32_e32 v103, v2
	v_mov_b32_e32 v104, v2
	v_mov_b32_e32 v105, v2
	v_mov_b32_e32 v106, v2
	v_mov_b32_e32 v107, v2
	v_mov_b32_e32 v108, v2
	v_mov_b32_e32 v109, v2
	v_mov_b32_e32 v118, v2
	v_mov_b32_e32 v119, v2
	v_mov_b32_e32 v120, v2
	v_mov_b32_e32 v121, v2
	v_mov_b32_e32 v78, v2
	v_mov_b32_e32 v79, v2
	v_mov_b32_e32 v80, v2
	v_mov_b32_e32 v81, v2
	v_mov_b32_e32 v82, v2
	v_mov_b32_e32 v83, v2
	v_mov_b32_e32 v84, v2
	v_mov_b32_e32 v85, v2
	v_mov_b32_e32 v94, v2
	v_mov_b32_e32 v95, v2
	v_mov_b32_e32 v96, v2
	v_mov_b32_e32 v97, v2
	v_mov_b32_e32 v98, v2
	v_mov_b32_e32 v99, v2
	v_mov_b32_e32 v100, v2
	v_mov_b32_e32 v101, v2
	v_mov_b32_e32 v110, v2
	v_mov_b32_e32 v111, v2
	v_mov_b32_e32 v112, v2
	v_mov_b32_e32 v113, v2
	v_mov_b32_e32 v114, v2
	v_mov_b32_e32 v115, v2
	v_mov_b32_e32 v116, v2
	v_mov_b32_e32 v117, v2
	v_mov_b32_e32 v122, v2
	v_mov_b32_e32 v123, v2
	v_mov_b32_e32 v124, v2
	v_mov_b32_e32 v125, v2
	v_mov_b32_e32 v126, v2
	v_mov_b32_e32 v127, v2
	v_mov_b32_e32 v128, v2
	v_mov_b32_e32 v129, v2
	.p2align	6

.LBB0_557:
	s_ashr_i32 s19, s18, 31
	s_lshl_b64 s[20:21], s[18:19], 19
	s_add_u32 s20, s3, s20
	s_addc_u32 s21, s33, s21
	s_and_b64 s[22:23], s[4:5], exec
	s_cselect_b32 s2, s21, s27
	s_cselect_b32 s7, s20, s26
	s_ashr_i32 s17, s16, 31
	s_lshl_b64 s[22:23], s[16:17], 19
	s_add_u32 s22, s34, s22
	s_addc_u32 s23, s35, s23
	s_and_b64 s[30:31], s[4:5], exec
	s_cselect_b32 s17, s23, s29
	s_cselect_b32 s19, s22, s28
	s_add_u32 s26, s26, 0x40080
	s_addc_u32 s27, s27, 0
	s_add_u32 s25, s28, 0x100
	v_mov_b32_e32 v2, 0
	s_addc_u32 s51, s29, 0
	s_mov_b32 s52, -2
	v_mov_b32_e32 v3, v2
	v_mov_b32_e32 v4, v2
	v_mov_b32_e32 v5, v2
	v_mov_b32_e32 v6, v2
	v_mov_b32_e32 v7, v2
	v_mov_b32_e32 v8, v2
	v_mov_b32_e32 v9, v2
	v_mov_b32_e32 v14, v2
	v_mov_b32_e32 v15, v2
	v_mov_b32_e32 v16, v2
	v_mov_b32_e32 v17, v2
	v_mov_b32_e32 v22, v2
	v_mov_b32_e32 v23, v2
	v_mov_b32_e32 v24, v2
	v_mov_b32_e32 v25, v2
	v_mov_b32_e32 v30, v2
	v_mov_b32_e32 v31, v2
	v_mov_b32_e32 v32, v2
	v_mov_b32_e32 v33, v2
	v_mov_b32_e32 v38, v2
	v_mov_b32_e32 v39, v2
	v_mov_b32_e32 v40, v2
	v_mov_b32_e32 v41, v2
	v_mov_b32_e32 v46, v2
	v_mov_b32_e32 v47, v2
	v_mov_b32_e32 v48, v2
	v_mov_b32_e32 v49, v2
	v_mov_b32_e32 v54, v2
	v_mov_b32_e32 v55, v2
	v_mov_b32_e32 v56, v2
	v_mov_b32_e32 v57, v2
	v_mov_b32_e32 v10, v2
	v_mov_b32_e32 v11, v2
	v_mov_b32_e32 v12, v2
	v_mov_b32_e32 v13, v2
	v_mov_b32_e32 v18, v2
	v_mov_b32_e32 v19, v2
	v_mov_b32_e32 v20, v2
	v_mov_b32_e32 v21, v2
	v_mov_b32_e32 v26, v2
	v_mov_b32_e32 v27, v2
	v_mov_b32_e32 v28, v2
	v_mov_b32_e32 v29, v2
	v_mov_b32_e32 v34, v2
	v_mov_b32_e32 v35, v2
	v_mov_b32_e32 v36, v2
	v_mov_b32_e32 v37, v2
	v_mov_b32_e32 v42, v2
	v_mov_b32_e32 v43, v2
	v_mov_b32_e32 v44, v2
	v_mov_b32_e32 v45, v2
	v_mov_b32_e32 v50, v2
	v_mov_b32_e32 v51, v2
	v_mov_b32_e32 v52, v2
	v_mov_b32_e32 v53, v2
	v_mov_b32_e32 v58, v2
	v_mov_b32_e32 v59, v2
	v_mov_b32_e32 v60, v2
	v_mov_b32_e32 v61, v2
	v_mov_b32_e32 v62, v2
	v_mov_b32_e32 v63, v2
	v_mov_b32_e32 v64, v2
	v_mov_b32_e32 v65, v2
	v_mov_b32_e32 v66, v2
	v_mov_b32_e32 v67, v2
	v_mov_b32_e32 v68, v2
	v_mov_b32_e32 v69, v2
	v_mov_b32_e32 v70, v2
	v_mov_b32_e32 v71, v2
	v_mov_b32_e32 v72, v2
	v_mov_b32_e32 v73, v2
	v_mov_b32_e32 v78, v2
	v_mov_b32_e32 v79, v2
	v_mov_b32_e32 v80, v2
	v_mov_b32_e32 v81, v2
	v_mov_b32_e32 v86, v2
	v_mov_b32_e32 v87, v2
	v_mov_b32_e32 v88, v2
	v_mov_b32_e32 v89, v2
	v_mov_b32_e32 v94, v2
	v_mov_b32_e32 v95, v2
	v_mov_b32_e32 v96, v2
	v_mov_b32_e32 v97, v2
	v_mov_b32_e32 v102, v2
	v_mov_b32_e32 v103, v2
	v_mov_b32_e32 v104, v2
	v_mov_b32_e32 v105, v2
	v_mov_b32_e32 v110, v2
	v_mov_b32_e32 v111, v2
	v_mov_b32_e32 v112, v2
	v_mov_b32_e32 v113, v2
	v_mov_b32_e32 v118, v2
	v_mov_b32_e32 v119, v2
	v_mov_b32_e32 v120, v2
	v_mov_b32_e32 v121, v2
	v_mov_b32_e32 v74, v2
	v_mov_b32_e32 v75, v2
	v_mov_b32_e32 v76, v2
	v_mov_b32_e32 v77, v2
	v_mov_b32_e32 v82, v2
	v_mov_b32_e32 v83, v2
	v_mov_b32_e32 v84, v2
	v_mov_b32_e32 v85, v2
	v_mov_b32_e32 v90, v2
	v_mov_b32_e32 v91, v2
	v_mov_b32_e32 v92, v2
	v_mov_b32_e32 v93, v2
	v_mov_b32_e32 v98, v2
	v_mov_b32_e32 v99, v2
	v_mov_b32_e32 v100, v2
	v_mov_b32_e32 v101, v2
	v_mov_b32_e32 v106, v2
	v_mov_b32_e32 v107, v2
	v_mov_b32_e32 v108, v2
	v_mov_b32_e32 v109, v2
	v_mov_b32_e32 v114, v2
	v_mov_b32_e32 v115, v2
	v_mov_b32_e32 v116, v2
	v_mov_b32_e32 v117, v2
	v_mov_b32_e32 v122, v2
	v_mov_b32_e32 v123, v2
	v_mov_b32_e32 v124, v2
	v_mov_b32_e32 v125, v2
	v_mov_b32_e32 v126, v2
	v_mov_b32_e32 v127, v2
	v_mov_b32_e32 v128, v2
	v_mov_b32_e32 v129, v2
	.p2align	6

.Lnoprio_925:
	s_movk_i32 s99, 0x4800
	v_lshlrev_b32_e32 v136, 1, v160
	s_barrier
	s_branch .LBB0_926
	.p2align	6

.LBB0_1100:
	s_ashr_i32 s19, s18, 31
	s_lshl_b64 s[20:21], s[18:19], 19
	s_add_u32 s20, s33, s20
	s_addc_u32 s21, s36, s21
	s_and_b64 s[22:23], s[4:5], exec
	s_cselect_b32 s2, s21, s27
	s_cselect_b32 s19, s20, s26
	s_ashr_i32 s17, s16, 31
	s_lshl_b64 s[22:23], s[16:17], 19
	s_add_u32 s22, s8, s22
	s_addc_u32 s23, s9, s23
	s_and_b64 s[30:31], s[4:5], exec
	s_cselect_b32 s17, s23, s29
	s_cselect_b32 s51, s22, s28
	s_add_u32 s52, s28, 0x100
	v_mov_b32_e32 v2, 0
	s_addc_u32 s53, s29, 0
	s_mov_b32 s54, -2
	v_mov_b32_e32 v3, v2
	v_mov_b32_e32 v4, v2
	v_mov_b32_e32 v5, v2
	v_mov_b32_e32 v6, v2
	v_mov_b32_e32 v7, v2
	v_mov_b32_e32 v8, v2
	v_mov_b32_e32 v9, v2
	v_mov_b32_e32 v18, v2
	v_mov_b32_e32 v19, v2
	v_mov_b32_e32 v20, v2
	v_mov_b32_e32 v21, v2
	v_mov_b32_e32 v22, v2
	v_mov_b32_e32 v23, v2
	v_mov_b32_e32 v24, v2
	v_mov_b32_e32 v25, v2
	v_mov_b32_e32 v34, v2
	v_mov_b32_e32 v35, v2
	v_mov_b32_e32 v36, v2
	v_mov_b32_e32 v37, v2
	v_mov_b32_e32 v38, v2
	v_mov_b32_e32 v39, v2
	v_mov_b32_e32 v40, v2
	v_mov_b32_e32 v41, v2
	v_mov_b32_e32 v50, v2
	v_mov_b32_e32 v51, v2
	v_mov_b32_e32 v52, v2
	v_mov_b32_e32 v53, v2
	v_mov_b32_e32 v54, v2
	v_mov_b32_e32 v55, v2
	v_mov_b32_e32 v56, v2
	v_mov_b32_e32 v57, v2
	v_mov_b32_e32 v10, v2
	v_mov_b32_e32 v11, v2
	v_mov_b32_e32 v12, v2
	v_mov_b32_e32 v13, v2
	v_mov_b32_e32 v14, v2
	v_mov_b32_e32 v15, v2
	v_mov_b32_e32 v16, v2
	v_mov_b32_e32 v17, v2
	v_mov_b32_e32 v26, v2
	v_mov_b32_e32 v27, v2
	v_mov_b32_e32 v28, v2
	v_mov_b32_e32 v29, v2
	v_mov_b32_e32 v30, v2
	v_mov_b32_e32 v31, v2
	v_mov_b32_e32 v32, v2
	v_mov_b32_e32 v33, v2
	v_mov_b32_e32 v42, v2
	v_mov_b32_e32 v43, v2
	v_mov_b32_e32 v44, v2
	v_mov_b32_e32 v45, v2
	v_mov_b32_e32 v46, v2
	v_mov_b32_e32 v47, v2
	v_mov_b32_e32 v48, v2
	v_mov_b32_e32 v49, v2
	v_mov_b32_e32 v62, v2
	v_mov_b32_e32 v63, v2
	v_mov_b32_e32 v64, v2
	v_mov_b32_e32 v65, v2
	v_mov_b32_e32 v66, v2
	v_mov_b32_e32 v67, v2
	v_mov_b32_e32 v68, v2
	v_mov_b32_e32 v69, v2
	v_mov_b32_e32 v70, v2
	v_mov_b32_e32 v71, v2
	v_mov_b32_e32 v72, v2
	v_mov_b32_e32 v73, v2
	v_mov_b32_e32 v74, v2
	v_mov_b32_e32 v75, v2
	v_mov_b32_e32 v76, v2
	v_mov_b32_e32 v77, v2
	v_mov_b32_e32 v82, v2
	v_mov_b32_e32 v83, v2
	v_mov_b32_e32 v84, v2
	v_mov_b32_e32 v85, v2
	v_mov_b32_e32 v90, v2
	v_mov_b32_e32 v91, v2
	v_mov_b32_e32 v92, v2
	v_mov_b32_e32 v93, v2
	v_mov_b32_e32 v98, v2
	v_mov_b32_e32 v99, v2
	v_mov_b32_e32 v100, v2
	v_mov_b32_e32 v101, v2
	v_mov_b32_e32 v106, v2
	v_mov_b32_e32 v107, v2
	v_mov_b32_e32 v108, v2
	v_mov_b32_e32 v109, v2
	v_mov_b32_e32 v126, v2
	v_mov_b32_e32 v127, v2
	v_mov_b32_e32 v128, v2
	v_mov_b32_e32 v129, v2
	v_mov_b32_e32 v134, v2
	v_mov_b32_e32 v135, v2
	v_mov_b32_e32 v136, v2
	v_mov_b32_e32 v137, v2
	v_mov_b32_e32 v78, v2
	v_mov_b32_e32 v79, v2
	v_mov_b32_e32 v80, v2
	v_mov_b32_e32 v81, v2
	v_mov_b32_e32 v86, v2
	v_mov_b32_e32 v87, v2
	v_mov_b32_e32 v88, v2
	v_mov_b32_e32 v89, v2
	v_mov_b32_e32 v94, v2
	v_mov_b32_e32 v95, v2
	v_mov_b32_e32 v96, v2
	v_mov_b32_e32 v97, v2
	v_mov_b32_e32 v102, v2
	v_mov_b32_e32 v103, v2
	v_mov_b32_e32 v104, v2
	v_mov_b32_e32 v105, v2
	v_mov_b32_e32 v118, v2
	v_mov_b32_e32 v119, v2
	v_mov_b32_e32 v120, v2
	v_mov_b32_e32 v121, v2
	v_mov_b32_e32 v130, v2
	v_mov_b32_e32 v131, v2
	v_mov_b32_e32 v132, v2
	v_mov_b32_e32 v133, v2
	v_mov_b32_e32 v138, v2
	v_mov_b32_e32 v139, v2
	v_mov_b32_e32 v140, v2
	v_mov_b32_e32 v141, v2
	v_mov_b32_e32 v142, v2
	v_mov_b32_e32 v143, v2
	v_mov_b32_e32 v144, v2
	v_mov_b32_e32 v145, v2
	.p2align	6

.LBB0_1366:
	s_add_u32 s2, s22, 0x100
	v_mov_b32_e32 v2, 0
	s_addc_u32 s49, s23, 0
	s_mov_b32 s50, -2
	v_mov_b32_e32 v3, v2
	v_mov_b32_e32 v4, v2
	v_mov_b32_e32 v5, v2
	v_mov_b32_e32 v6, v2
	v_mov_b32_e32 v7, v2
	v_mov_b32_e32 v8, v2
	v_mov_b32_e32 v9, v2
	v_mov_b32_e32 v18, v2
	v_mov_b32_e32 v19, v2
	v_mov_b32_e32 v20, v2
	v_mov_b32_e32 v21, v2
	v_mov_b32_e32 v22, v2
	v_mov_b32_e32 v23, v2
	v_mov_b32_e32 v24, v2
	v_mov_b32_e32 v25, v2
	v_mov_b32_e32 v34, v2
	v_mov_b32_e32 v35, v2
	v_mov_b32_e32 v36, v2
	v_mov_b32_e32 v37, v2
	v_mov_b32_e32 v38, v2
	v_mov_b32_e32 v39, v2
	v_mov_b32_e32 v40, v2
	v_mov_b32_e32 v41, v2
	v_mov_b32_e32 v50, v2
	v_mov_b32_e32 v51, v2
	v_mov_b32_e32 v52, v2
	v_mov_b32_e32 v53, v2
	v_mov_b32_e32 v54, v2
	v_mov_b32_e32 v55, v2
	v_mov_b32_e32 v56, v2
	v_mov_b32_e32 v57, v2
	v_mov_b32_e32 v10, v2
	v_mov_b32_e32 v11, v2
	v_mov_b32_e32 v12, v2
	v_mov_b32_e32 v13, v2
	v_mov_b32_e32 v14, v2
	v_mov_b32_e32 v15, v2
	v_mov_b32_e32 v16, v2
	v_mov_b32_e32 v17, v2
	v_mov_b32_e32 v26, v2
	v_mov_b32_e32 v27, v2
	v_mov_b32_e32 v28, v2
	v_mov_b32_e32 v29, v2
	v_mov_b32_e32 v30, v2
	v_mov_b32_e32 v31, v2
	v_mov_b32_e32 v32, v2
	v_mov_b32_e32 v33, v2
	v_mov_b32_e32 v42, v2
	v_mov_b32_e32 v43, v2
	v_mov_b32_e32 v44, v2
	v_mov_b32_e32 v45, v2
	v_mov_b32_e32 v46, v2
	v_mov_b32_e32 v47, v2
	v_mov_b32_e32 v48, v2
	v_mov_b32_e32 v49, v2
	v_mov_b32_e32 v58, v2
	v_mov_b32_e32 v59, v2
	v_mov_b32_e32 v60, v2
	v_mov_b32_e32 v61, v2
	v_mov_b32_e32 v62, v2
	v_mov_b32_e32 v63, v2
	v_mov_b32_e32 v64, v2
	v_mov_b32_e32 v65, v2
	v_mov_b32_e32 v66, v2
	v_mov_b32_e32 v67, v2
	v_mov_b32_e32 v68, v2
	v_mov_b32_e32 v69, v2
	v_mov_b32_e32 v70, v2
	v_mov_b32_e32 v71, v2
	v_mov_b32_e32 v72, v2
	v_mov_b32_e32 v73, v2
	v_mov_b32_e32 v82, v2
	v_mov_b32_e32 v83, v2
	v_mov_b32_e32 v84, v2
	v_mov_b32_e32 v85, v2
	v_mov_b32_e32 v86, v2
	v_mov_b32_e32 v87, v2
	v_mov_b32_e32 v88, v2
	v_mov_b32_e32 v89, v2
	v_mov_b32_e32 v94, v2
	v_mov_b32_e32 v95, v2
	v_mov_b32_e32 v96, v2
	v_mov_b32_e32 v97, v2
	v_mov_b32_e32 v102, v2
	v_mov_b32_e32 v103, v2
	v_mov_b32_e32 v104, v2
	v_mov_b32_e32 v105, v2
	v_mov_b32_e32 v110, v2
	v_mov_b32_e32 v111, v2
	v_mov_b32_e32 v112, v2
	v_mov_b32_e32 v113, v2
	v_mov_b32_e32 v118, v2
	v_mov_b32_e32 v119, v2
	v_mov_b32_e32 v120, v2
	v_mov_b32_e32 v121, v2
	v_mov_b32_e32 v74, v2
	v_mov_b32_e32 v75, v2
	v_mov_b32_e32 v76, v2
	v_mov_b32_e32 v77, v2
	v_mov_b32_e32 v78, v2
	v_mov_b32_e32 v79, v2
	v_mov_b32_e32 v80, v2
	v_mov_b32_e32 v81, v2
	v_mov_b32_e32 v90, v2
	v_mov_b32_e32 v91, v2
	v_mov_b32_e32 v92, v2
	v_mov_b32_e32 v93, v2
	v_mov_b32_e32 v98, v2
	v_mov_b32_e32 v99, v2
	v_mov_b32_e32 v100, v2
	v_mov_b32_e32 v101, v2
	v_mov_b32_e32 v106, v2
	v_mov_b32_e32 v107, v2
	v_mov_b32_e32 v108, v2
	v_mov_b32_e32 v109, v2
	v_mov_b32_e32 v114, v2
	v_mov_b32_e32 v115, v2
	v_mov_b32_e32 v116, v2
	v_mov_b32_e32 v117, v2
	v_mov_b32_e32 v122, v2
	v_mov_b32_e32 v123, v2
	v_mov_b32_e32 v124, v2
	v_mov_b32_e32 v125, v2
	v_mov_b32_e32 v126, v2
	v_mov_b32_e32 v127, v2
	v_mov_b32_e32 v128, v2
	v_mov_b32_e32 v129, v2
	.p2align	6

.Lnoprio_2159:
	s_movk_i32 s99, 0x4800
	v_lshlrev_b32_e32 v134, 1, v158
	s_barrier
	s_branch .LBB0_2160
	.p2align	6

.LBB0_2327:
	s_ashr_i32 s15, s14, 31
	s_lshl_b64 s[16:17], s[14:15], 19
	s_add_u32 s16, s30, s16
	s_addc_u32 s17, s31, s17
	s_and_b64 s[18:19], s[4:5], exec
	s_cselect_b32 s2, s17, s23
	s_cselect_b32 s15, s16, s22
	s_ashr_i32 s13, s12, 31
	s_lshl_b64 s[18:19], s[12:13], 19
	s_add_u32 s18, s33, s18
	s_addc_u32 s19, s34, s19
	s_and_b64 s[26:27], s[4:5], exec
	s_cselect_b32 s13, s19, s25
	s_cselect_b32 s52, s18, s24
	s_add_u32 s53, s24, 0x100
	v_mov_b32_e32 v2, 0
	s_addc_u32 s54, s25, 0
	s_mov_b32 s55, -2
	v_mov_b32_e32 v3, v2
	v_mov_b32_e32 v4, v2
	v_mov_b32_e32 v5, v2
	v_mov_b32_e32 v6, v2
	v_mov_b32_e32 v7, v2
	v_mov_b32_e32 v8, v2
	v_mov_b32_e32 v9, v2
	v_mov_b32_e32 v14, v2
	v_mov_b32_e32 v15, v2
	v_mov_b32_e32 v16, v2
	v_mov_b32_e32 v17, v2
	v_mov_b32_e32 v22, v2
	v_mov_b32_e32 v23, v2
	v_mov_b32_e32 v24, v2
	v_mov_b32_e32 v25, v2
	v_mov_b32_e32 v34, v2
	v_mov_b32_e32 v35, v2
	v_mov_b32_e32 v36, v2
	v_mov_b32_e32 v37, v2
	v_mov_b32_e32 v38, v2
	v_mov_b32_e32 v39, v2
	v_mov_b32_e32 v40, v2
	v_mov_b32_e32 v41, v2
	v_mov_b32_e32 v50, v2
	v_mov_b32_e32 v51, v2
	v_mov_b32_e32 v52, v2
	v_mov_b32_e32 v53, v2
	v_mov_b32_e32 v54, v2
	v_mov_b32_e32 v55, v2
	v_mov_b32_e32 v56, v2
	v_mov_b32_e32 v57, v2
	v_mov_b32_e32 v10, v2
	v_mov_b32_e32 v11, v2
	v_mov_b32_e32 v12, v2
	v_mov_b32_e32 v13, v2
	v_mov_b32_e32 v18, v2
	v_mov_b32_e32 v19, v2
	v_mov_b32_e32 v20, v2
	v_mov_b32_e32 v21, v2
	v_mov_b32_e32 v26, v2
	v_mov_b32_e32 v27, v2
	v_mov_b32_e32 v28, v2
	v_mov_b32_e32 v29, v2
	v_mov_b32_e32 v30, v2
	v_mov_b32_e32 v31, v2
	v_mov_b32_e32 v32, v2
	v_mov_b32_e32 v33, v2
	v_mov_b32_e32 v42, v2
	v_mov_b32_e32 v43, v2
	v_mov_b32_e32 v44, v2
	v_mov_b32_e32 v45, v2
	v_mov_b32_e32 v46, v2
	v_mov_b32_e32 v47, v2
	v_mov_b32_e32 v48, v2
	v_mov_b32_e32 v49, v2
	v_mov_b32_e32 v58, v2
	v_mov_b32_e32 v59, v2
	v_mov_b32_e32 v60, v2
	v_mov_b32_e32 v61, v2
	v_mov_b32_e32 v62, v2
	v_mov_b32_e32 v63, v2
	v_mov_b32_e32 v64, v2
	v_mov_b32_e32 v65, v2
	v_mov_b32_e32 v66, v2
	v_mov_b32_e32 v67, v2
	v_mov_b32_e32 v68, v2
	v_mov_b32_e32 v69, v2
	v_mov_b32_e32 v70, v2
	v_mov_b32_e32 v71, v2
	v_mov_b32_e32 v72, v2
	v_mov_b32_e32 v73, v2
	v_mov_b32_e32 v78, v2
	v_mov_b32_e32 v79, v2
	v_mov_b32_e32 v80, v2
	v_mov_b32_e32 v81, v2
	v_mov_b32_e32 v90, v2
	v_mov_b32_e32 v91, v2
	v_mov_b32_e32 v92, v2
	v_mov_b32_e32 v93, v2
	v_mov_b32_e32 v98, v2
	v_mov_b32_e32 v99, v2
	v_mov_b32_e32 v100, v2
	v_mov_b32_e32 v101, v2
	v_mov_b32_e32 v106, v2
	v_mov_b32_e32 v107, v2
	v_mov_b32_e32 v108, v2
	v_mov_b32_e32 v109, v2
	v_mov_b32_e32 v114, v2
	v_mov_b32_e32 v115, v2
	v_mov_b32_e32 v116, v2
	v_mov_b32_e32 v117, v2
	v_mov_b32_e32 v122, v2
	v_mov_b32_e32 v123, v2
	v_mov_b32_e32 v124, v2
	v_mov_b32_e32 v125, v2
	v_mov_b32_e32 v74, v2
	v_mov_b32_e32 v75, v2
	v_mov_b32_e32 v76, v2
	v_mov_b32_e32 v77, v2
	v_mov_b32_e32 v82, v2
	v_mov_b32_e32 v83, v2
	v_mov_b32_e32 v84, v2
	v_mov_b32_e32 v85, v2
	v_mov_b32_e32 v94, v2
	v_mov_b32_e32 v95, v2
	v_mov_b32_e32 v96, v2
	v_mov_b32_e32 v97, v2
	v_mov_b32_e32 v102, v2
	v_mov_b32_e32 v103, v2
	v_mov_b32_e32 v104, v2
	v_mov_b32_e32 v105, v2
	v_mov_b32_e32 v110, v2
	v_mov_b32_e32 v111, v2
	v_mov_b32_e32 v112, v2
	v_mov_b32_e32 v113, v2
	v_mov_b32_e32 v118, v2
	v_mov_b32_e32 v119, v2
	v_mov_b32_e32 v120, v2
	v_mov_b32_e32 v121, v2
	v_mov_b32_e32 v134, v2
	v_mov_b32_e32 v135, v2
	v_mov_b32_e32 v136, v2
	v_mov_b32_e32 v137, v2
	v_mov_b32_e32 v142, v2
	v_mov_b32_e32 v143, v2
	v_mov_b32_e32 v144, v2
	v_mov_b32_e32 v145, v2
	.p2align	6

.LBB0_2485:
	s_ashr_i32 s17, s16, 31
	s_lshl_b64 s[18:19], s[16:17], 19
	s_add_u32 s18, s3, s18
	s_addc_u32 s19, s30, s19
	s_and_b64 s[20:21], s[4:5], exec
	s_cselect_b32 s17, s19, s25
	s_cselect_b32 s48, s18, s24
	s_ashr_i32 s15, s14, 31
	s_lshl_b64 s[20:21], s[14:15], 19
	s_add_u32 s20, s31, s20
	s_addc_u32 s21, s33, s21
	s_and_b64 s[28:29], s[4:5], exec
	s_cselect_b32 s15, s21, s27
	s_cselect_b32 s49, s20, s26
	s_add_u32 s24, s24, 0x40080
	s_addc_u32 s25, s25, 0
	s_add_u32 s50, s26, 0x100
	v_mov_b32_e32 v2, 0
	s_addc_u32 s51, s27, 0
	s_mov_b32 s52, -2
	v_mov_b32_e32 v3, v2
	v_mov_b32_e32 v4, v2
	v_mov_b32_e32 v5, v2
	v_mov_b32_e32 v6, v2
	v_mov_b32_e32 v7, v2
	v_mov_b32_e32 v8, v2
	v_mov_b32_e32 v9, v2
	v_mov_b32_e32 v18, v2
	v_mov_b32_e32 v19, v2
	v_mov_b32_e32 v20, v2
	v_mov_b32_e32 v21, v2
	v_mov_b32_e32 v22, v2
	v_mov_b32_e32 v23, v2
	v_mov_b32_e32 v24, v2
	v_mov_b32_e32 v25, v2
	v_mov_b32_e32 v34, v2
	v_mov_b32_e32 v35, v2
	v_mov_b32_e32 v36, v2
	v_mov_b32_e32 v37, v2
	v_mov_b32_e32 v38, v2
	v_mov_b32_e32 v39, v2
	v_mov_b32_e32 v40, v2
	v_mov_b32_e32 v41, v2
	v_mov_b32_e32 v50, v2
	v_mov_b32_e32 v51, v2
	v_mov_b32_e32 v52, v2
	v_mov_b32_e32 v53, v2
	v_mov_b32_e32 v54, v2
	v_mov_b32_e32 v55, v2
	v_mov_b32_e32 v56, v2
	v_mov_b32_e32 v57, v2
	v_mov_b32_e32 v10, v2
	v_mov_b32_e32 v11, v2
	v_mov_b32_e32 v12, v2
	v_mov_b32_e32 v13, v2
	v_mov_b32_e32 v14, v2
	v_mov_b32_e32 v15, v2
	v_mov_b32_e32 v16, v2
	v_mov_b32_e32 v17, v2
	v_mov_b32_e32 v26, v2
	v_mov_b32_e32 v27, v2
	v_mov_b32_e32 v28, v2
	v_mov_b32_e32 v29, v2
	v_mov_b32_e32 v30, v2
	v_mov_b32_e32 v31, v2
	v_mov_b32_e32 v32, v2
	v_mov_b32_e32 v33, v2
	v_mov_b32_e32 v42, v2
	v_mov_b32_e32 v43, v2
	v_mov_b32_e32 v44, v2
	v_mov_b32_e32 v45, v2
	v_mov_b32_e32 v46, v2
	v_mov_b32_e32 v47, v2
	v_mov_b32_e32 v48, v2
	v_mov_b32_e32 v49, v2
	v_mov_b32_e32 v58, v2
	v_mov_b32_e32 v59, v2
	v_mov_b32_e32 v60, v2
	v_mov_b32_e32 v61, v2
	v_mov_b32_e32 v62, v2
	v_mov_b32_e32 v63, v2
	v_mov_b32_e32 v64, v2
	v_mov_b32_e32 v65, v2
	v_mov_b32_e32 v66, v2
	v_mov_b32_e32 v67, v2
	v_mov_b32_e32 v68, v2
	v_mov_b32_e32 v69, v2
	v_mov_b32_e32 v70, v2
	v_mov_b32_e32 v71, v2
	v_mov_b32_e32 v72, v2
	v_mov_b32_e32 v73, v2
	v_mov_b32_e32 v82, v2
	v_mov_b32_e32 v83, v2
	v_mov_b32_e32 v84, v2
	v_mov_b32_e32 v85, v2
	v_mov_b32_e32 v86, v2
	v_mov_b32_e32 v87, v2
	v_mov_b32_e32 v88, v2
	v_mov_b32_e32 v89, v2
	v_mov_b32_e32 v98, v2
	v_mov_b32_e32 v99, v2
	v_mov_b32_e32 v100, v2
	v_mov_b32_e32 v101, v2
	v_mov_b32_e32 v102, v2
	v_mov_b32_e32 v103, v2
	v_mov_b32_e32 v104, v2
	v_mov_b32_e32 v105, v2
	v_mov_b32_e32 v114, v2
	v_mov_b32_e32 v115, v2
	v_mov_b32_e32 v116, v2
	v_mov_b32_e32 v117, v2
	v_mov_b32_e32 v118, v2
	v_mov_b32_e32 v119, v2
	v_mov_b32_e32 v120, v2
	v_mov_b32_e32 v121, v2
	v_mov_b32_e32 v74, v2
	v_mov_b32_e32 v75, v2
	v_mov_b32_e32 v76, v2
	v_mov_b32_e32 v77, v2
	v_mov_b32_e32 v78, v2
	v_mov_b32_e32 v79, v2
	v_mov_b32_e32 v80, v2
	v_mov_b32_e32 v81, v2
	v_mov_b32_e32 v90, v2
	v_mov_b32_e32 v91, v2
	v_mov_b32_e32 v92, v2
	v_mov_b32_e32 v93, v2
	v_mov_b32_e32 v94, v2
	v_mov_b32_e32 v95, v2
	v_mov_b32_e32 v96, v2
	v_mov_b32_e32 v97, v2
	v_mov_b32_e32 v106, v2
	v_mov_b32_e32 v107, v2
	v_mov_b32_e32 v108, v2
	v_mov_b32_e32 v109, v2
	v_mov_b32_e32 v110, v2
	v_mov_b32_e32 v111, v2
	v_mov_b32_e32 v112, v2
	v_mov_b32_e32 v113, v2
	v_mov_b32_e32 v122, v2
	v_mov_b32_e32 v123, v2
	v_mov_b32_e32 v124, v2
	v_mov_b32_e32 v125, v2
	v_mov_b32_e32 v126, v2
	v_mov_b32_e32 v127, v2
	v_mov_b32_e32 v128, v2
	v_mov_b32_e32 v129, v2
	.p2align	6

.LBB0_2582:
	s_add_u32 s2, s18, 0x100
	v_mov_b32_e32 v2, 0
	s_addc_u32 s50, s19, 0
	s_mov_b32 s51, -2
	v_mov_b32_e32 v3, v2
	v_mov_b32_e32 v4, v2
	v_mov_b32_e32 v5, v2
	v_mov_b32_e32 v6, v2
	v_mov_b32_e32 v7, v2
	v_mov_b32_e32 v8, v2
	v_mov_b32_e32 v9, v2
	v_mov_b32_e32 v14, v2
	v_mov_b32_e32 v15, v2
	v_mov_b32_e32 v16, v2
	v_mov_b32_e32 v17, v2
	v_mov_b32_e32 v22, v2
	v_mov_b32_e32 v23, v2
	v_mov_b32_e32 v24, v2
	v_mov_b32_e32 v25, v2
	v_mov_b32_e32 v30, v2
	v_mov_b32_e32 v31, v2
	v_mov_b32_e32 v32, v2
	v_mov_b32_e32 v33, v2
	v_mov_b32_e32 v38, v2
	v_mov_b32_e32 v39, v2
	v_mov_b32_e32 v40, v2
	v_mov_b32_e32 v41, v2
	v_mov_b32_e32 v50, v2
	v_mov_b32_e32 v51, v2
	v_mov_b32_e32 v52, v2
	v_mov_b32_e32 v53, v2
	v_mov_b32_e32 v54, v2
	v_mov_b32_e32 v55, v2
	v_mov_b32_e32 v56, v2
	v_mov_b32_e32 v57, v2
	v_mov_b32_e32 v10, v2
	v_mov_b32_e32 v11, v2
	v_mov_b32_e32 v12, v2
	v_mov_b32_e32 v13, v2
	v_mov_b32_e32 v18, v2
	v_mov_b32_e32 v19, v2
	v_mov_b32_e32 v20, v2
	v_mov_b32_e32 v21, v2
	v_mov_b32_e32 v26, v2
	v_mov_b32_e32 v27, v2
	v_mov_b32_e32 v28, v2
	v_mov_b32_e32 v29, v2
	v_mov_b32_e32 v34, v2
	v_mov_b32_e32 v35, v2
	v_mov_b32_e32 v36, v2
	v_mov_b32_e32 v37, v2
	v_mov_b32_e32 v42, v2
	v_mov_b32_e32 v43, v2
	v_mov_b32_e32 v44, v2
	v_mov_b32_e32 v45, v2
	v_mov_b32_e32 v46, v2
	v_mov_b32_e32 v47, v2
	v_mov_b32_e32 v48, v2
	v_mov_b32_e32 v49, v2
	v_mov_b32_e32 v58, v2
	v_mov_b32_e32 v59, v2
	v_mov_b32_e32 v60, v2
	v_mov_b32_e32 v61, v2
	v_mov_b32_e32 v62, v2
	v_mov_b32_e32 v63, v2
	v_mov_b32_e32 v64, v2
	v_mov_b32_e32 v65, v2
	v_mov_b32_e32 v66, v2
	v_mov_b32_e32 v67, v2
	v_mov_b32_e32 v68, v2
	v_mov_b32_e32 v69, v2
	v_mov_b32_e32 v70, v2
	v_mov_b32_e32 v71, v2
	v_mov_b32_e32 v72, v2
	v_mov_b32_e32 v73, v2
	v_mov_b32_e32 v82, v2
	v_mov_b32_e32 v83, v2
	v_mov_b32_e32 v84, v2
	v_mov_b32_e32 v85, v2
	v_mov_b32_e32 v86, v2
	v_mov_b32_e32 v87, v2
	v_mov_b32_e32 v88, v2
	v_mov_b32_e32 v89, v2
	v_mov_b32_e32 v94, v2
	v_mov_b32_e32 v95, v2
	v_mov_b32_e32 v96, v2
	v_mov_b32_e32 v97, v2
	v_mov_b32_e32 v102, v2
	v_mov_b32_e32 v103, v2
	v_mov_b32_e32 v104, v2
	v_mov_b32_e32 v105, v2
	v_mov_b32_e32 v110, v2
	v_mov_b32_e32 v111, v2
	v_mov_b32_e32 v112, v2
	v_mov_b32_e32 v113, v2
	v_mov_b32_e32 v118, v2
	v_mov_b32_e32 v119, v2
	v_mov_b32_e32 v120, v2
	v_mov_b32_e32 v121, v2
	v_mov_b32_e32 v74, v2
	v_mov_b32_e32 v75, v2
	v_mov_b32_e32 v76, v2
	v_mov_b32_e32 v77, v2
	v_mov_b32_e32 v78, v2
	v_mov_b32_e32 v79, v2
	v_mov_b32_e32 v80, v2
	v_mov_b32_e32 v81, v2
	v_mov_b32_e32 v90, v2
	v_mov_b32_e32 v91, v2
	v_mov_b32_e32 v92, v2
	v_mov_b32_e32 v93, v2
	v_mov_b32_e32 v98, v2
	v_mov_b32_e32 v99, v2
	v_mov_b32_e32 v100, v2
	v_mov_b32_e32 v101, v2
	v_mov_b32_e32 v106, v2
	v_mov_b32_e32 v107, v2
	v_mov_b32_e32 v108, v2
	v_mov_b32_e32 v109, v2
	v_mov_b32_e32 v114, v2
	v_mov_b32_e32 v115, v2
	v_mov_b32_e32 v116, v2
	v_mov_b32_e32 v117, v2
	v_mov_b32_e32 v122, v2
	v_mov_b32_e32 v123, v2
	v_mov_b32_e32 v124, v2
	v_mov_b32_e32 v125, v2
	v_mov_b32_e32 v126, v2
	v_mov_b32_e32 v127, v2
	v_mov_b32_e32 v128, v2
	v_mov_b32_e32 v129, v2
	.p2align	6
